# carried-state copies (outputs only) moved from the layer-0 FFN-down tail to the last layer's FFN-down tail, where 224 workgroups and HBM are otherwise idle
# speedup vs baseline: 1.0134x; 1.0059x over previous
; __device__ __forceinline__ PItem p0_decode(const Args& a, int it) {
;     constexpr int I_IN = 16 * 96, I_OUT = 16 * 32, I_W1 = 16 * 88, I_W2 = 44 * 32, I_LAYER = I_IN + I_OUT + 2 * I_W1 + I_W2;
;     const int l = it / I_LAYER, e = l >> 1, odd = l & 1; int r = it % I_LAYER;
;     unsigned char* wl = a.ws + WS_W + (size_t)l * W_LAYER; float* cv = (float*)(a.ws + WS_CVEC) + (size_t)l * CVEC_LAYER;
;     PItem p;
;     if (r < I_IN) { const int kb = r / 96, nb = r % 96; p.W = (odd ? a.in[13] : a.in[5]) + (size_t)e * D * EIN; p.N = EIN; p.K = D; p.g = l > 0 ? a.in[21] + (size_t)(l - 1) * D : nullptr; p.be = l > 0 ? a.in[22] + (size_t)(l - 1) * D : nullptr;
;         p.WT = (bf16*)(wl + W_IN); p.drow0 = in_dst_row(32 * nb, odd); p.k0 = 64 * kb; p.n0 = 32 * nb; p.c1 = cv; p.c2 = cv + EIN; return p; } r -= I_IN;
;     if (r < I_OUT) { const int kb = r / 32, nb = r % 32; p.W = (odd ? a.in[15] : a.in[6]) + (size_t)e * D * D; p.N = D; p.K = D; p.g = nullptr; p.be = nullptr;
;         p.WT = (bf16*)(wl + W_OUT); p.drow0 = 32 * nb; p.k0 = 64 * kb; p.n0 = 32 * nb; p.c1 = nullptr; p.c2 = nullptr; return p; } r -= I_OUT;
;     if (r < 2 * I_W1) { const int second = r >= I_W1; if (second) r -= I_W1; const int kb = r / 88, nb = r % 88, n0 = 32 * nb; p.W = (second ? a.in[17] : a.in[16]) + (size_t)l * D * DFF; p.N = DFF; p.K = D;
; __global__ void __launch_bounds__(NWAVES * 64, 2) mk_fwd(Args args) {
;     ...
;                 { int Gq = F.G; asm volatile("" : "+s"(Gq)); const int nmu = g.N >> 5, mfirst = (nmu <= Gq / 2 || Gq < 256) ? (Gq - nmu > 0 ? Gq - nmu : 0) : Gq / 2; for (int mu = (int)blockIdx.x - mfirst; mu >= 0 && mu < nmu; mu += Gq - mfirst) pg8::mini_ring(F.lds + RING_OFF, g.A, g.Bt, g.K, E, mu, F.wave);
;                   if (l < 3) { if (mfirst > 0) { if ((int)blockIdx.x < mfirst) { p_convert_tail(F, args, (l + 1) * P_ILAYER, (l + 2) * P_ILAYER - ((F.G == 256) ? (l == 0 ? 768 : 1792) : 0), (int)blockIdx.x, mfirst); if (l == 0) p_state_copies_tail(F, args, (int)blockIdx.x, mfirst); } }
;                   else { p_convert_tail(F, args, (l + 1) * P_ILAYER, (l + 2) * P_ILAYER - ((F.G == 256) ? (l == 0 ? 768 : 1792) : 0), (int)blockIdx.x, F.G); if (l == 0) p_state_copies_tail(F, args, (int)blockIdx.x, F.G); } } } }
;             if (l < 3) SEAM_LT(pb + 5); else SEAM(pb + 5);
.LBB0_1546:
	s_waitcnt vmcnt(24)
	s_barrier
	v_readlane_b32 s0, v255, 62
	s_cmp_lg_u32 s0, 3
	s_mov_b64 s[10:11], -1
	v_readlane_b32 s1, v255, 63
	s_cmp_lt_i32 s29, 33
	s_cbranch_scc0 .LBB0_1627
	v_readlane_b32 s0, v255, 62
	v_readlane_b32 s1, v255, 63
	s_mul_i32 s2, s0, 0x1880
	v_readlane_b32 s0, v255, 53
	v_readlane_b32 s1, v255, 54
	s_and_b64 s[0:1], s[0:1], exec
	s_movk_i32 s0, 0xfb00
	s_cselect_b32 s7, s0, 0xfffff500
	v_readlane_b32 s0, v252, 62
	v_readlane_b32 s1, v252, 63
	s_and_b64 s[0:1], s[0:1], exec
	s_cselect_b32 s0, s7, 0
	s_add_i32 s7, s2, s0
	v_readlane_b32 s0, v253, 60
	s_addk_i32 s7, 0x3100
	v_mbcnt_lo_u32_b32 v0, -1, 0
	v_mbcnt_hi_u32_b32 v0, -1, v0
	s_add_i32 s29, s0, s2
	v_add_u32_e32 v0, s75, v0
	s_cmp_ge_i32 s29, s7
	s_cbranch_scc1 .LBB0_1601
	s_mul_hi_i32 s0, s29, 0x5397829d
	s_lshr_b32 s1, s0, 31
	s_ashr_i32 s0, s0, 11
	s_add_i32 s26, s0, s1
	s_mul_i32 s1, s26, 0x1880
	s_ashr_i32 s30, s26, 1
	s_and_b32 s0, s26, 1
	s_sub_i32 s1, s29, s1
	s_ashr_i32 s27, s26, 31
	s_mul_i32 s10, s26, 0x1880000
	v_readlane_b32 s11, v253, 5
	s_mul_hi_i32 s2, s26, 0x1880000
	s_add_u32 s22, s11, s10
	v_readlane_b32 s10, v253, 6
	s_addc_u32 s23, s10, s2
	s_mul_i32 s10, s26, 0x11000
	v_readlane_b32 s11, v253, 7
	s_mul_hi_i32 s2, s26, 0x11000
	s_add_u32 s24, s11, s10
	v_readlane_b32 s10, v253, 8
	s_addc_u32 s25, s10, s2
	s_cmpk_gt_i32 s1, 0x5ff
	s_mov_b64 s[46:47], -1
	s_cbranch_scc0 .LBB0_1558
	s_cmpk_gt_u32 s1, 0x7ff
	s_cbranch_scc0 .LBB0_1555
	s_mov_b64 s[18:19], -1
	s_cmpk_gt_u32 s1, 0x12ff
	s_mul_hi_i32 s2, s26, 0xb00000
	s_mul_i32 s13, s26, 0xb00000
	s_cbranch_scc0 .LBB0_1553
	v_readlane_b32 s56, v253, 26
	v_readlane_b32 s57, v253, 27
	s_add_u32 s10, s56, s13
	s_addc_u32 s11, s57, s2
	s_add_u32 s14, s22, 0x1300000
	s_addc_u32 s15, s23, 0
	s_lshl_b32 s16, s1, 1
	s_lshl_b32 s12, s1, 5
	s_and_b32 s16, s16, 0x7fffffc0
	v_readlane_b32 s58, v253, 28
	v_readlane_b32 s59, v253, 29
	v_readlane_b32 s60, v253, 30
	v_readlane_b32 s61, v253, 31
	v_readlane_b32 s62, v253, 32
	v_readlane_b32 s63, v253, 33
	s_and_b32 s12, s12, 0x3e0
	s_addk_i32 s16, 0xda00
	s_mov_b64 s[18:19], 0

; __device__ __forceinline__ PItem p0_decode(const Args& a, int it) {
;     constexpr int I_IN = 16 * 96, I_OUT = 16 * 32, I_W1 = 16 * 88, I_W2 = 44 * 32, I_LAYER = I_IN + I_OUT + 2 * I_W1 + I_W2;
;     const int l = it / I_LAYER, e = l >> 1, odd = l & 1; int r = it % I_LAYER;
;     unsigned char* wl = a.ws + WS_W + (size_t)l * W_LAYER; float* cv = (float*)(a.ws + WS_CVEC) + (size_t)l * CVEC_LAYER;
;     PItem p;
;     if (r < I_IN) { const int kb = r / 96, nb = r % 96; p.W = (odd ? a.in[13] : a.in[5]) + (size_t)e * D * EIN; p.N = EIN; p.K = D; p.g = l > 0 ? a.in[21] + (size_t)(l - 1) * D : nullptr; p.be = l > 0 ? a.in[22] + (size_t)(l - 1) * D : nullptr;
;         p.WT = (bf16*)(wl + W_IN); p.drow0 = in_dst_row(32 * nb, odd); p.k0 = 64 * kb; p.n0 = 32 * nb; p.c1 = cv; p.c2 = cv + EIN; return p; } r -= I_IN;
;     if (r < I_OUT) { const int kb = r / 32, nb = r % 32; p.W = (odd ? a.in[15] : a.in[6]) + (size_t)e * D * D; p.N = D; p.K = D; p.g = nullptr; p.be = nullptr;
;         p.WT = (bf16*)(wl + W_OUT); p.drow0 = 32 * nb; p.k0 = 64 * kb; p.n0 = 32 * nb; p.c1 = nullptr; p.c2 = nullptr; return p; } r -= I_OUT;
;     if (r < 2 * I_W1) { const int second = r >= I_W1; if (second) r -= I_W1; const int kb = r / 88, nb = r % 88, n0 = 32 * nb; p.W = (second ? a.in[17] : a.in[16]) + (size_t)l * D * DFF; p.N = DFF; p.K = D;
; __global__ void __launch_bounds__(NWAVES * 64, 2) mk_fwd(Args args) {
;     ...
;                 { int Gq = F.G; asm volatile("" : "+s"(Gq)); const int nmu = g.N >> 5, mfirst = (nmu <= Gq / 2 || Gq < 256) ? (Gq - nmu > 0 ? Gq - nmu : 0) : Gq / 2; for (int mu = (int)blockIdx.x - mfirst; mu >= 0 && mu < nmu; mu += Gq - mfirst) pg8::mini_ring(F.lds + RING_OFF, g.A, g.Bt, g.K, E, mu, F.wave);
;                   if (l < 3) { if (mfirst > 0) { if ((int)blockIdx.x < mfirst) { p_convert_tail(F, args, (l + 1) * P_ILAYER, (l + 2) * P_ILAYER - ((F.G == 256) ? (l == 0 ? 768 : 1792) : 0), (int)blockIdx.x, mfirst); if (l == 0) p_state_copies_tail(F, args, (int)blockIdx.x, mfirst); } }
;                   else { p_convert_tail(F, args, (l + 1) * P_ILAYER, (l + 2) * P_ILAYER - ((F.G == 256) ? (l == 0 ? 768 : 1792) : 0), (int)blockIdx.x, F.G); if (l == 0) p_state_copies_tail(F, args, (int)blockIdx.x, F.G); } } } }
;             if (l < 3) SEAM_LT(pb + 5); else SEAM(pb + 5);
.LBB0_1627:
	s_and_b64 vcc, exec, s[10:11]
	s_cbranch_vccz .LBB0_1707
	v_readlane_b32 s0, v254, 27
	s_cmp_ge_i32 s0, s28
	v_readlane_b32 s1, v254, 28
	s_cbranch_scc1 .LBB0_1707
	v_readlane_b32 s0, v255, 62
	s_cmp_eq_u32 s0, 3
	s_cbranch_scc1 .LBB0_1682
	v_readlane_b32 s0, v255, 62
	v_readlane_b32 s1, v255, 63
	s_mul_i32 s2, s0, 0x1880
	v_readlane_b32 s0, v255, 53
	v_readlane_b32 s1, v255, 54
	s_and_b64 s[0:1], s[0:1], exec
	s_movk_i32 s0, 0xfb00
	s_cselect_b32 s7, s0, 0xfffff500
	v_readlane_b32 s0, v252, 62
	v_readlane_b32 s1, v252, 63
	s_and_b64 s[0:1], s[0:1], exec
	s_cselect_b32 s0, s7, 0
	s_add_i32 s7, s2, s0
	v_readlane_b32 s0, v253, 60
	s_addk_i32 s7, 0x3100
	v_mbcnt_lo_u32_b32 v0, -1, 0
	v_mbcnt_hi_u32_b32 v0, -1, v0
	s_add_i32 s29, s0, s2
	v_add_u32_e32 v0, s75, v0
	s_cmp_ge_i32 s29, s7
	s_cbranch_scc1 .LBB0_1682
	s_mul_hi_i32 s0, s29, 0x5397829d
	s_lshr_b32 s1, s0, 31
	s_ashr_i32 s0, s0, 11
	s_add_i32 s26, s0, s1
	s_mul_i32 s1, s26, 0x1880
	s_ashr_i32 s30, s26, 1
	s_and_b32 s0, s26, 1
	s_sub_i32 s1, s29, s1
	s_ashr_i32 s27, s26, 31
	s_mul_i32 s10, s26, 0x1880000
	v_readlane_b32 s11, v253, 5
	s_mul_hi_i32 s2, s26, 0x1880000
	s_add_u32 s22, s11, s10
	v_readlane_b32 s10, v253, 6
	s_addc_u32 s23, s10, s2
	s_mul_i32 s10, s26, 0x11000
	v_readlane_b32 s11, v253, 7
	s_mul_hi_i32 s2, s26, 0x11000
	s_add_u32 s24, s11, s10
	v_readlane_b32 s10, v253, 8
	s_addc_u32 s25, s10, s2
	v_readlane_b32 s48, v250, 0
	s_cmpk_gt_i32 s1, 0x5ff
	s_mov_b64 s[46:47], -1
	v_readlane_b32 s49, v250, 1
	s_cbranch_scc0 .LBB0_1639
	s_cmpk_gt_u32 s1, 0x7ff
	s_cbranch_scc0 .LBB0_1636
	s_mov_b64 s[18:19], -1
	s_cmpk_gt_u32 s1, 0x12ff
	s_mul_hi_i32 s2, s26, 0xb00000
	s_mul_i32 s13, s26, 0xb00000
	s_cbranch_scc0 .LBB0_1634
	v_readlane_b32 s56, v253, 26
	v_readlane_b32 s57, v253, 27
	s_add_u32 s10, s56, s13
	s_addc_u32 s11, s57, s2
	s_add_u32 s14, s22, 0x1300000
	s_addc_u32 s15, s23, 0
	s_lshl_b32 s16, s1, 1
	s_lshl_b32 s12, s1, 5
	s_and_b32 s16, s16, 0x7fffffc0
	v_readlane_b32 s58, v253, 28
	v_readlane_b32 s59, v253, 29
	v_readlane_b32 s60, v253, 30
	v_readlane_b32 s61, v253, 31
	v_readlane_b32 s62, v253, 32
	v_readlane_b32 s63, v253, 33
	s_and_b32 s12, s12, 0x3e0
	s_addk_i32 s16, 0xda00
	s_mov_b64 s[18:19], 0

; __device__ __forceinline__ void st16_wt(void* p, f32x4 v) { asm volatile("global_store_dwordx4 %0, %1, off sc1\n\ts_nop 1" :: "v"(p), "v"(v) : "memory"); }
; __device__ __forceinline__ Frame phase_frame(const Frame& F0) { Frame F = F0; int t = F0.wave * 64 + lane_id_now(); asm volatile("" : "+v"(t)); F.tid = t; F.lane = t & 63; F.wave = F0.wave; return F; }
; __device__ __forceinline__ void p_state_copies_tail(const Frame& F0, const Args& a, int wg_idx, int n_wgs) {
;     const Frame F = phase_frame(F0);
;     const size_t gt = ((size_t)wg_idx * NWAVES + F.wave) * 64 + F.lane, NGT = (size_t)n_wgs * NWAVES * 64;
;     float* o_cs = a.out + (size_t)MT * D + (size_t)2 * NB * NH * DK * DV + (size_t)2 * NB * 30 * CW + (size_t)2 * NB * 2 * D + (size_t)2 * DEC * NH * DK * DV;
;     float* o_ss = o_cs + (size_t)2 * DEC * 30 * CW;
;     constexpr size_t NC = (size_t)2 * DEC * 29 * (CW / 4);
;     for (size_t i0 = gt; i0 < NC; i0 += 4 * NGT) { f32x4 t[4];
; #pragma unroll
;         for (int q = 0; q < 4; ++q) { const size_t i = i0 + q * NGT; if (i < NC) { const size_t c4 = i % (CW / 4), r = i / (CW / 4), ii = r % 29, eb = r / 29; t[q] = __builtin_nontemporal_load((const f32x4*)(a.in[3] + (eb * 30 + ii + 1) * CW + c4 * 4)); } }
; #pragma unroll
;         for (int q = 0; q < 4; ++q) { const size_t i = i0 + q * NGT; if (i < NC) { const size_t c4 = i % (CW / 4), r = i / (CW / 4), ii = r % 29, eb = r / 29; st16_wt(o_cs + (eb * 30 + ii) * CW + c4 * 4, t[q]); } } }
;     for (size_t i = gt; i < (size_t)2 * DEC * (D / 4); i += NGT) { const size_t c4 = i % (D / 4), eb = i / (D / 4);
;         *(f32x4*)(o_ss + (eb * 2 + 0) * D + c4 * 4) = *(const f32x4*)(a.in[4] + (eb * 2 + 1) * D + c4 * 4); }
.LBB0_1682:
	v_readlane_b32 s0, v255, 53
	v_readlane_b32 s1, v255, 54
	v_readlane_b32 s76, v255, 18
	v_readlane_b32 s78, v255, 20
	v_readlane_b32 s80, v255, 22
	v_readlane_b32 s82, v255, 24
	v_readlane_b32 s86, v255, 26
	v_readlane_b32 s52, v255, 32
	v_readlane_b32 s0, v255, 62
	s_cmp_lg_u32 s0, 3
	s_cselect_b64 vcc, -1, 0
	v_readlane_b32 s77, v255, 19
	v_readlane_b32 s79, v255, 21
	v_readlane_b32 s81, v255, 23
	v_readlane_b32 s83, v255, 25
	v_readlane_b32 s87, v255, 27
	v_readlane_b32 s48, v255, 30
	v_readlane_b32 s53, v255, 33
	s_mov_b64 s[18:19], 0xffff
	v_readlane_b32 s49, v255, 31
	s_cbranch_vccnz .LBB0_1707
	v_readlane_b32 s0, v254, 61
	v_mbcnt_lo_u32_b32 v0, -1, 0
	v_mbcnt_hi_u32_b32 v0, -1, v0
	v_readlane_b32 s1, v254, 62
	v_add_u32_e32 v0, s75, v0
	s_andn2_b64 vcc, exec, s[0:1]
	v_readlane_b32 s0, v254, 63
	s_waitcnt lgkmcnt(0)
	v_mov_b32_e32 v21, v1
	v_and_b32_e32 v20, 63, v0
	v_readlane_b32 s1, v255, 0
	s_mov_b32 s29, s3
	s_lshl_b64 s[16:17], s[28:29], 9
	v_lshl_add_u64 v[22:23], s[0:1], 0, v[20:21]
	v_lshlrev_b64 v[18:19], 2, v[22:23]
	s_cbranch_vccnz .LBB0_1703
	s_lshl_b32 s0, s90, 11
	s_lshl_b64 s[18:19], s[28:29], 11
	s_add_i32 s7, s0, 0xffff0000
	s_lshl_b64 s[0:1], s[28:29], 10
	v_readlane_b32 s64, v254, 63
	v_readlane_b32 s65, v255, 0
	s_add_u32 s20, s64, s0
	s_addc_u32 s21, s65, s1
	s_lshl_b32 s0, s90, 10
	v_readlane_b32 s1, v254, 51
	s_add_i32 s2, s1, s0
	s_mul_i32 s1, s28, 0x600
	s_mul_hi_u32 s0, s28, 0x600
	s_add_u32 s22, s64, s1
	s_addc_u32 s23, s65, s0
	s_mul_i32 s0, s90, 0x600
	v_readlane_b32 s1, v254, 52
	s_add_i32 s40, s1, s0
	s_add_u32 s24, s64, s16
	s_addc_u32 s25, s65, s17
	s_lshl_b32 s0, s90, 9
	v_readlane_b32 s1, v254, 53
	s_waitcnt vmcnt(0)
	v_mov_b32_e32 v2, 0
	v_readlane_b32 s60, v255, 3
	s_mov_b32 s41, s3
	s_add_i32 s46, s1, s0
	s_mov_b32 s47, s3
	v_lshlrev_b64 v[24:25], 2, v[22:23]
	s_lshl_b64 s[26:27], s[28:29], 13
	s_mov_b64 s[30:31], 0
	s_mov_b64 s[34:35], s[2:3]
	v_readlane_b32 s61, v255, 4
	v_mov_b32_e32 v3, v2
	v_mov_b32_e32 v4, v2
	v_mov_b32_e32 v5, v2
	v_mov_b32_e32 v6, v2
	v_mov_b32_e32 v7, v2
	v_mov_b32_e32 v8, v2
	v_mov_b32_e32 v9, v2
	v_mov_b32_e32 v10, v2
	v_mov_b32_e32 v11, v2
	v_mov_b32_e32 v12, v2
	v_mov_b32_e32 v13, v2
	v_mov_b32_e32 v14, v2
	v_mov_b32_e32 v15, v2
	v_mov_b32_e32 v16, v2
	v_mov_b32_e32 v17, v2
	s_branch .LBB0_1686

; #define SEAM(k) do { XcdBarrier _b; _b.bar = (unsigned*)(args.ws + WS_CTL) + CW_BAR; _b.x = xb_xcc_id(); _b.st = (volatile LAS unsigned*)(F.lds + MISC_OFF) + 8; xcd_barrier(_b); } while (0)
; #define SEAM_LT(k) do { XcdBarrier _b; _b.bar = (unsigned*)(args.ws + WS_CTL) + CW_BAR; _b.x = xb_xcc_id(); _b.st = (volatile LAS unsigned*)(F.lds + MISC_OFF) + 8; xcd_barrier_light(_b, (const unsigned*)(args.ws + WS_CTL) + CW_NONLOC); } while (0)
; __global__ void __launch_bounds__(NWAVES * 64, 2) mk_fwd(Args args) {
;     ...
;                   if (l < 3) { if (mfirst > 0) { if ((int)blockIdx.x < mfirst) { p_convert_tail(F, args, (l + 1) * P_ILAYER, (l + 2) * P_ILAYER - ((F.G == 256) ? (l == 0 ? 768 : 1792) : 0), (int)blockIdx.x, mfirst); if (l == 0) p_state_copies_tail(F, args, (int)blockIdx.x, mfirst); } }
;                   else { p_convert_tail(F, args, (l + 1) * P_ILAYER, (l + 2) * P_ILAYER - ((F.G == 256) ? (l == 0 ? 768 : 1792) : 0), (int)blockIdx.x, F.G); if (l == 0) p_state_copies_tail(F, args, (int)blockIdx.x, F.G); } } } }
;             if (l < 3) SEAM_LT(pb + 5); else SEAM(pb + 5);
.LBB0_1707:
	v_readlane_b32 s0, v255, 62
	s_cmp_eq_u32 s0, 3
	s_cbranch_scc0 .Lsc_light
	s_mov_b64 s[10:11], -1
	s_branch .LBB0_1764
